# loop-edge edit extended to the W_out GEMM K-loop (control scalars in the shadow of the last MFMAs)
# baseline (speedup 1.0000x reference)
; #define PG8_STAGE(bufoff, gbase, voff) do { _Pragma("unroll") for (int _i = 0; _i < 2; ++_i) \
;         __builtin_amdgcn_global_load_lds((const unsigned*)((const char*)(gbase) + (voff)[_i]), (PG8_LAS unsigned*)(lds + (bufoff) + ldsw + _i * 8192), 16, 0, 0); } while (0)
; #define PG8_LDA(dst, b, h) do { _Pragma("unroll") for (int m = 0; m < 4; ++m) _Pragma("unroll") for (int k = 0; k < 2; ++k) dst[m][k] = *(const PG8_LAS bf16x8*)(lds + PG8_SA(b, h) + aoff + m * 2048 + k * 1024); } while (0)
; #define PG8_LDB(dst, b, h) do { _Pragma("unroll") for (int n = 0; n < 2; ++n) _Pragma("unroll") for (int k = 0; k < 2; ++k) dst[n][k] = *(const PG8_LAS bf16x8*)(lds + PG8_SB(b, h) + boff + n * 2048 + k * 1024); } while (0)
; #define PG8_MMA(ai, bj, At, Bt) do { __builtin_amdgcn_s_setprio(1); _Pragma("unroll") for (int m = 0; m < 4; ++m) _Pragma("unroll") for (int n = 0; n < 2; ++n) _Pragma("unroll") for (int k = 0; k < 2; ++k) \
;         acc[ai][bj][m][n] = __builtin_amdgcn_mfma_f32_16x16x32_bf16(Bt[n][k], At[m][k], acc[ai][bj][m][n], 0, 0, 0); __builtin_amdgcn_s_setprio(0); } while (0)
; #define PG8_WAIT_V(n) asm volatile("s_waitcnt vmcnt(" #n ")" ::: "memory")
; #define PG8_WAIT_L(n) asm volatile("s_waitcnt lgkmcnt(" #n ")" ::: "memory")
; template <class Epi, class Sched, bool ALIGN_EPI = false, bool SP2 = false>
; __device__ __forceinline__ void gemm_phase(PG8_LAS unsigned char* lds, const Gemm g, const Sched S, const Epi E) {
;     ...
;             const bool last = (t == nt - 2);
;             const char* a1 = cA + (size_t)(t + 1) * kstep;
;             const char* a2 = last ? nA : cA + (size_t)(t + 2) * kstep; const char* b2 = last ? nB : cB + (size_t)(t + 2) * kstep;
;             const char* a3 = a2 + kstep; const char* b3 = b2 + kstep;
;             if (last && has_next) S.a_ready(nxt);
;             if constexpr (SP2) {
;             PG8_LDB(B0, 0, 0); PG8_LDB(B1, 0, 1); PG8_SCHED; PG8_LDA(At, 0, 0); PG8_STAGE(PG8_SA(1, 1), a1 + hstep, voffA);
;             PG8_WAIT_V(8); PG8_WAIT_L(0); PG8_BAR; PG8_MMA(0, 0, At, B0); PG8_MMA(0, 1, At, B1); PG8_BAR; PG8_SCHED;
;             PG8_LDA(At, 0, 1); PG8_STAGE(PG8_SB(0, 0), b2, voffB); PG8_STAGE(PG8_SB(0, 1), b2 + hstep, voffB); PG8_STAGE(PG8_SA(0, 0), a2, voffA);
;             PG8_WAIT_V(8); PG8_WAIT_L(0); PG8_BAR; PG8_MMA(1, 0, At, B0); PG8_MMA(1, 1, At, B1); PG8_BAR; PG8_SCHED;
.Lpagefit_5:
.LBB0_898:
	v_add_u32_e32 v1, s65, v170
	ds_read_b128 v[120:123], v1
	ds_read_b128 v[176:179], v1 offset:1024
	ds_read_b128 v[180:183], v1 offset:2048
	ds_read_b128 v[190:193], v1 offset:3072
	v_add_u32_e32 v1, s68, v170
	s_add_u32 s6, s66, s70
	ds_read_b128 v[194:197], v1
	ds_read_b128 v[198:201], v1 offset:1024
	ds_read_b128 v[202:205], v1 offset:2048
	ds_read_b128 v[206:209], v1 offset:3072
	s_addc_u32 s7, s67, s71
	s_add_u32 s6, s6, 0x100
	s_addc_u32 s7, s7, 0
	s_add_u32 s14, s74, s70
	s_addc_u32 s15, s75, s71
	s_cmpk_eq_i32 s70, 0x700
	s_cselect_b32 s11, s51, s7
	s_cselect_b32 s10, s72, s6
	s_cselect_b32 s7, s45, s15
	s_cselect_b32 s6, s73, s14
	v_lshl_add_u64 v[2:3], v[138:139], 0, s[70:71]
	s_add_i32 m0, s9, 0xc000
	ds_read_b128 v[210:213], v173
	ds_read_b128 v[214:217], v173 offset:1024
	ds_read_b128 v[218:221], v173 offset:2048
	ds_read_b128 v[222:225], v173 offset:3072
	ds_read_b128 v[226:229], v173 offset:4096
	ds_read_b128 v[230:233], v173 offset:5120
	ds_read_b128 v[234:237], v173 offset:6144
	ds_read_b128 v[238:241], v173 offset:7168
	global_load_lds_dwordx4 v[2:3], off
	v_lshl_add_u64 v[2:3], v[164:165], 0, s[70:71]
	s_add_i32 m0, s9, 0xe000
	s_nop 0
	global_load_lds_dwordx4 v[2:3], off
	s_waitcnt vmcnt(8)
	s_waitcnt lgkmcnt(0)
	s_barrier
	s_setprio 1
	s_waitcnt lgkmcnt(0)
	v_mfma_f32_16x16x32_bf16 v[144:147], v[120:123], v[210:213], v[144:147]
	v_mfma_f32_16x16x32_bf16 v[140:143], v[180:183], v[210:213], v[140:143]
	v_mfma_f32_16x16x32_bf16 v[112:115], v[120:123], v[218:221], v[112:115]
	v_mfma_f32_16x16x32_bf16 v[108:111], v[180:183], v[218:221], v[108:111]
	v_mfma_f32_16x16x32_bf16 v[96:99], v[120:123], v[226:229], v[96:99]
	v_mfma_f32_16x16x32_bf16 v[92:95], v[180:183], v[226:229], v[92:95]
	v_mfma_f32_16x16x32_bf16 v[80:83], v[120:123], v[234:237], v[80:83]
	v_mfma_f32_16x16x32_bf16 v[76:79], v[180:183], v[234:237], v[76:79]
	v_mfma_f32_16x16x32_bf16 v[144:147], v[176:179], v[214:217], v[144:147]
	v_mfma_f32_16x16x32_bf16 v[140:143], v[190:193], v[214:217], v[140:143]
	v_mfma_f32_16x16x32_bf16 v[112:115], v[176:179], v[222:225], v[112:115]
	v_mfma_f32_16x16x32_bf16 v[108:111], v[190:193], v[222:225], v[108:111]
	v_mfma_f32_16x16x32_bf16 v[96:99], v[176:179], v[230:233], v[96:99]
	v_mfma_f32_16x16x32_bf16 v[92:95], v[190:193], v[230:233], v[92:95]
	v_mfma_f32_16x16x32_bf16 v[80:83], v[176:179], v[238:241], v[80:83]
	v_mfma_f32_16x16x32_bf16 v[76:79], v[190:193], v[238:241], v[76:79]
	s_setprio 0
	s_setprio 1
	v_mfma_f32_16x16x32_bf16 v[124:127], v[194:197], v[210:213], v[124:127]
	v_mfma_f32_16x16x32_bf16 v[116:119], v[202:205], v[210:213], v[116:119]
	v_mfma_f32_16x16x32_bf16 v[104:107], v[194:197], v[218:221], v[104:107]
	v_mfma_f32_16x16x32_bf16 v[100:103], v[202:205], v[218:221], v[100:103]
	v_mfma_f32_16x16x32_bf16 v[88:91], v[194:197], v[226:229], v[88:91]
	v_mfma_f32_16x16x32_bf16 v[84:87], v[202:205], v[226:229], v[84:87]
	v_mfma_f32_16x16x32_bf16 v[72:75], v[194:197], v[234:237], v[72:75]
	v_mfma_f32_16x16x32_bf16 v[68:71], v[202:205], v[234:237], v[68:71]
	v_mfma_f32_16x16x32_bf16 v[124:127], v[198:201], v[214:217], v[124:127]
	v_mfma_f32_16x16x32_bf16 v[116:119], v[206:209], v[214:217], v[116:119]
	v_mfma_f32_16x16x32_bf16 v[104:107], v[198:201], v[222:225], v[104:107]
	v_mfma_f32_16x16x32_bf16 v[100:103], v[206:209], v[222:225], v[100:103]
	v_mfma_f32_16x16x32_bf16 v[88:91], v[198:201], v[230:233], v[88:91]
	v_mfma_f32_16x16x32_bf16 v[84:87], v[206:209], v[230:233], v[84:87]
	v_mfma_f32_16x16x32_bf16 v[72:75], v[198:201], v[238:241], v[72:75]
	v_mfma_f32_16x16x32_bf16 v[68:71], v[206:209], v[238:241], v[68:71]
	s_setprio 0
	s_barrier
	s_add_i32 s14, s65, s8
	v_lshl_add_u64 v[166:167], s[6:7], 0, v[150:151]
	s_mov_b32 m0, s14
	ds_read_b128 v[210:213], v173 offset:16384
	ds_read_b128 v[214:217], v173 offset:17408
	ds_read_b128 v[218:221], v173 offset:18432
	ds_read_b128 v[222:225], v173 offset:19456
	ds_read_b128 v[226:229], v173 offset:20480
	ds_read_b128 v[230:233], v173 offset:21504
	ds_read_b128 v[234:237], v173 offset:22528
	ds_read_b128 v[238:241], v173 offset:23552
	global_load_lds_dwordx4 v[166:167], off
	s_add_i32 m0, s14, 0x2000
	s_add_u32 s14, s6, 0x40000
	v_lshl_add_u64 v[184:185], s[6:7], 0, v[154:155]
	s_addc_u32 s15, s7, 0
	s_add_i32 s77, s68, s8
	global_load_lds_dwordx4 v[184:185], off
	v_lshl_add_u64 v[2:3], s[14:15], 0, v[150:151]
	s_mov_b32 m0, s77
	v_lshl_add_u64 v[186:187], s[10:11], 0, v[148:149]
	global_load_lds_dwordx4 v[2:3], off
	v_lshl_add_u64 v[2:3], s[14:15], 0, v[154:155]
	s_add_i32 m0, s77, 0x2000
	v_lshl_add_u64 v[242:243], s[10:11], 0, v[152:153]
	global_load_lds_dwordx4 v[2:3], off
	s_mov_b32 m0, s9
	s_nop 0
	global_load_lds_dwordx4 v[186:187], off
	s_mov_b32 m0, s12
	s_nop 0
	global_load_lds_dwordx4 v[242:243], off
	s_waitcnt vmcnt(8)
	s_waitcnt lgkmcnt(0)
	s_barrier
; #define PG8_STAGE(bufoff, gbase, voff) do { _Pragma("unroll") for (int _i = 0; _i < 2; ++_i) \
;         __builtin_amdgcn_global_load_lds((const unsigned*)((const char*)(gbase) + (voff)[_i]), (PG8_LAS unsigned*)(lds + (bufoff) + ldsw + _i * 8192), 16, 0, 0); } while (0)
; #define PG8_LDA(dst, b, h) do { _Pragma("unroll") for (int m = 0; m < 4; ++m) _Pragma("unroll") for (int k = 0; k < 2; ++k) dst[m][k] = *(const PG8_LAS bf16x8*)(lds + PG8_SA(b, h) + aoff + m * 2048 + k * 1024); } while (0)
; #define PG8_LDB(dst, b, h) do { _Pragma("unroll") for (int n = 0; n < 2; ++n) _Pragma("unroll") for (int k = 0; k < 2; ++k) dst[n][k] = *(const PG8_LAS bf16x8*)(lds + PG8_SB(b, h) + boff + n * 2048 + k * 1024); } while (0)
; #define PG8_MMA(ai, bj, At, Bt) do { __builtin_amdgcn_s_setprio(1); _Pragma("unroll") for (int m = 0; m < 4; ++m) _Pragma("unroll") for (int n = 0; n < 2; ++n) _Pragma("unroll") for (int k = 0; k < 2; ++k) \
;         acc[ai][bj][m][n] = __builtin_amdgcn_mfma_f32_16x16x32_bf16(Bt[n][k], At[m][k], acc[ai][bj][m][n], 0, 0, 0); __builtin_amdgcn_s_setprio(0); } while (0)
; #define PG8_WAIT_V(n) asm volatile("s_waitcnt vmcnt(" #n ")" ::: "memory")
; #define PG8_WAIT_L(n) asm volatile("s_waitcnt lgkmcnt(" #n ")" ::: "memory")
; #define PG8_BAR __builtin_amdgcn_s_barrier()
; #define PG8_SCHED __builtin_amdgcn_sched_barrier(0)
; template <class Epi, class Sched, bool ALIGN_EPI = false, bool SP2 = false>
; __device__ __forceinline__ void gemm_phase(PG8_LAS unsigned char* lds, const Gemm g, const Sched S, const Epi E) {
;     ...
;             PG8_WAIT_V(8); PG8_WAIT_L(0); PG8_BAR; PG8_MMA(1, 0, At, B0); PG8_MMA(1, 1, At, B1); PG8_BAR; PG8_SCHED;
;             PG8_LDB(B0, 1, 0); PG8_LDB(B1, 1, 1); PG8_SCHED; PG8_LDA(At, 1, 0); PG8_STAGE(PG8_SA(0, 1), a2 + hstep, voffA);
;             PG8_WAIT_V(8); PG8_WAIT_L(0); PG8_BAR; PG8_MMA(0, 0, At, B0); PG8_MMA(0, 1, At, B1); PG8_BAR; PG8_SCHED;
	s_setprio 1
	s_waitcnt lgkmcnt(0)
	v_mfma_f32_16x16x32_bf16 v[64:67], v[120:123], v[210:213], v[64:67]
	v_mfma_f32_16x16x32_bf16 v[60:63], v[180:183], v[210:213], v[60:63]
	v_mfma_f32_16x16x32_bf16 v[48:51], v[120:123], v[218:221], v[48:51]
	v_mfma_f32_16x16x32_bf16 v[44:47], v[180:183], v[218:221], v[44:47]
	v_mfma_f32_16x16x32_bf16 v[32:35], v[120:123], v[226:229], v[32:35]
	v_mfma_f32_16x16x32_bf16 v[28:31], v[180:183], v[226:229], v[28:31]
	v_mfma_f32_16x16x32_bf16 v[16:19], v[120:123], v[234:237], v[16:19]
	v_mfma_f32_16x16x32_bf16 v[12:15], v[180:183], v[234:237], v[12:15]
	v_mfma_f32_16x16x32_bf16 v[64:67], v[176:179], v[214:217], v[64:67]
	v_mfma_f32_16x16x32_bf16 v[60:63], v[190:193], v[214:217], v[60:63]
	v_mfma_f32_16x16x32_bf16 v[48:51], v[176:179], v[222:225], v[48:51]
	v_mfma_f32_16x16x32_bf16 v[44:47], v[190:193], v[222:225], v[44:47]
	v_mfma_f32_16x16x32_bf16 v[32:35], v[176:179], v[230:233], v[32:35]
	v_mfma_f32_16x16x32_bf16 v[28:31], v[190:193], v[230:233], v[28:31]
	v_mfma_f32_16x16x32_bf16 v[16:19], v[176:179], v[238:241], v[16:19]
	v_mfma_f32_16x16x32_bf16 v[12:15], v[190:193], v[238:241], v[12:15]
	s_setprio 0
	s_setprio 1
	v_mfma_f32_16x16x32_bf16 v[56:59], v[194:197], v[210:213], v[56:59]
	v_mfma_f32_16x16x32_bf16 v[52:55], v[202:205], v[210:213], v[52:55]
	v_mfma_f32_16x16x32_bf16 v[40:43], v[194:197], v[218:221], v[40:43]
	v_mfma_f32_16x16x32_bf16 v[36:39], v[202:205], v[218:221], v[36:39]
	v_mfma_f32_16x16x32_bf16 v[24:27], v[194:197], v[226:229], v[24:27]
	v_mfma_f32_16x16x32_bf16 v[20:23], v[202:205], v[226:229], v[20:23]
	v_mfma_f32_16x16x32_bf16 v[8:11], v[194:197], v[234:237], v[8:11]
	v_mfma_f32_16x16x32_bf16 v[2:5], v[202:205], v[234:237], v[4:7]
	v_mfma_f32_16x16x32_bf16 v[56:59], v[198:201], v[214:217], v[56:59]
	v_mfma_f32_16x16x32_bf16 v[52:55], v[206:209], v[214:217], v[52:55]
	v_mfma_f32_16x16x32_bf16 v[40:43], v[198:201], v[222:225], v[40:43]
	v_mfma_f32_16x16x32_bf16 v[36:39], v[206:209], v[222:225], v[36:39]
	v_mfma_f32_16x16x32_bf16 v[24:27], v[198:201], v[230:233], v[24:27]
	v_mfma_f32_16x16x32_bf16 v[20:23], v[206:209], v[230:233], v[20:23]
	v_mfma_f32_16x16x32_bf16 v[8:11], v[198:201], v[238:241], v[8:11]
	v_mfma_f32_16x16x32_bf16 v[2:5], v[206:209], v[238:241], v[2:5]
	s_setprio 0
	s_barrier
	s_add_i32 s14, 0, 0x18000
	v_add_u32_e32 v1, s14, v170
	s_add_i32 s15, 0, 0x1c000
	ds_read_b128 v[120:123], v1
	ds_read_b128 v[176:179], v1 offset:1024
	ds_read_b128 v[180:183], v1 offset:2048
	ds_read_b128 v[190:193], v1 offset:3072
	v_add_u32_e32 v1, s15, v170
	ds_read_b128 v[194:197], v1
	ds_read_b128 v[198:201], v1 offset:1024
	ds_read_b128 v[202:205], v1 offset:2048
	ds_read_b128 v[206:209], v1 offset:3072
	s_add_u32 s10, s10, 0x40000
	s_addc_u32 s11, s11, 0
	s_mov_b32 m0, s13
	v_lshl_add_u64 v[6:7], s[10:11], 0, v[148:149]
	ds_read_b128 v[210:213], v173 offset:32768
	ds_read_b128 v[214:217], v173 offset:33792
	ds_read_b128 v[218:221], v173 offset:34816
	ds_read_b128 v[222:225], v173 offset:35840
	ds_read_b128 v[226:229], v173 offset:36864
	ds_read_b128 v[230:233], v173 offset:37888
	ds_read_b128 v[234:237], v173 offset:38912
	ds_read_b128 v[238:241], v173 offset:39936
	global_load_lds_dwordx4 v[6:7], off
	v_lshl_add_u64 v[6:7], s[10:11], 0, v[152:153]
	s_mov_b32 m0, s33
	s_nop 0
	global_load_lds_dwordx4 v[6:7], off
	s_waitcnt vmcnt(8)
	s_waitcnt lgkmcnt(0)
	s_barrier
	s_setprio 1
	s_waitcnt lgkmcnt(0)
	v_mfma_f32_16x16x32_bf16 v[144:147], v[120:123], v[210:213], v[144:147]
	v_mfma_f32_16x16x32_bf16 v[140:143], v[180:183], v[210:213], v[140:143]
	v_mfma_f32_16x16x32_bf16 v[112:115], v[120:123], v[218:221], v[112:115]
	v_mfma_f32_16x16x32_bf16 v[108:111], v[180:183], v[218:221], v[108:111]
	v_mfma_f32_16x16x32_bf16 v[96:99], v[120:123], v[226:229], v[96:99]
	v_mfma_f32_16x16x32_bf16 v[92:95], v[180:183], v[226:229], v[92:95]
	v_mfma_f32_16x16x32_bf16 v[80:83], v[120:123], v[234:237], v[80:83]
	v_mfma_f32_16x16x32_bf16 v[76:79], v[180:183], v[234:237], v[76:79]
	v_mfma_f32_16x16x32_bf16 v[144:147], v[176:179], v[214:217], v[144:147]
	v_mfma_f32_16x16x32_bf16 v[140:143], v[190:193], v[214:217], v[140:143]
	v_mfma_f32_16x16x32_bf16 v[112:115], v[176:179], v[222:225], v[112:115]
	v_mfma_f32_16x16x32_bf16 v[108:111], v[190:193], v[222:225], v[108:111]
	v_mfma_f32_16x16x32_bf16 v[96:99], v[176:179], v[230:233], v[96:99]
	v_mfma_f32_16x16x32_bf16 v[92:95], v[190:193], v[230:233], v[92:95]
	v_mfma_f32_16x16x32_bf16 v[80:83], v[176:179], v[238:241], v[80:83]
	v_mfma_f32_16x16x32_bf16 v[76:79], v[190:193], v[238:241], v[76:79]
	s_setprio 0
	s_setprio 1
	v_mfma_f32_16x16x32_bf16 v[124:127], v[194:197], v[210:213], v[124:127]
	v_mfma_f32_16x16x32_bf16 v[116:119], v[202:205], v[210:213], v[116:119]
	v_mfma_f32_16x16x32_bf16 v[104:107], v[194:197], v[218:221], v[104:107]
	v_mfma_f32_16x16x32_bf16 v[100:103], v[202:205], v[218:221], v[100:103]
	v_mfma_f32_16x16x32_bf16 v[88:91], v[194:197], v[226:229], v[88:91]
	v_mfma_f32_16x16x32_bf16 v[84:87], v[202:205], v[226:229], v[84:87]
	v_mfma_f32_16x16x32_bf16 v[72:75], v[194:197], v[234:237], v[72:75]
	v_mfma_f32_16x16x32_bf16 v[68:71], v[202:205], v[234:237], v[68:71]
	v_mfma_f32_16x16x32_bf16 v[124:127], v[198:201], v[214:217], v[124:127]
	v_mfma_f32_16x16x32_bf16 v[116:119], v[206:209], v[214:217], v[116:119]
	v_mfma_f32_16x16x32_bf16 v[104:107], v[198:201], v[222:225], v[104:107]
	v_mfma_f32_16x16x32_bf16 v[100:103], v[206:209], v[222:225], v[100:103]
	v_mfma_f32_16x16x32_bf16 v[88:91], v[198:201], v[230:233], v[88:91]
	v_mfma_f32_16x16x32_bf16 v[84:87], v[206:209], v[230:233], v[84:87]
	v_mfma_f32_16x16x32_bf16 v[72:75], v[198:201], v[238:241], v[72:75]
	v_mfma_f32_16x16x32_bf16 v[68:71], v[206:209], v[238:241], v[68:71]
	s_setprio 0
	s_barrier
; #define PG8_STAGE(bufoff, gbase, voff) do { _Pragma("unroll") for (int _i = 0; _i < 2; ++_i) \
;         __builtin_amdgcn_global_load_lds((const unsigned*)((const char*)(gbase) + (voff)[_i]), (PG8_LAS unsigned*)(lds + (bufoff) + ldsw + _i * 8192), 16, 0, 0); } while (0)
; #define PG8_LDA(dst, b, h) do { _Pragma("unroll") for (int m = 0; m < 4; ++m) _Pragma("unroll") for (int k = 0; k < 2; ++k) dst[m][k] = *(const PG8_LAS bf16x8*)(lds + PG8_SA(b, h) + aoff + m * 2048 + k * 1024); } while (0)
; #define PG8_MMA(ai, bj, At, Bt) do { __builtin_amdgcn_s_setprio(1); _Pragma("unroll") for (int m = 0; m < 4; ++m) _Pragma("unroll") for (int n = 0; n < 2; ++n) _Pragma("unroll") for (int k = 0; k < 2; ++k) \
;         acc[ai][bj][m][n] = __builtin_amdgcn_mfma_f32_16x16x32_bf16(Bt[n][k], At[m][k], acc[ai][bj][m][n], 0, 0, 0); __builtin_amdgcn_s_setprio(0); } while (0)
; #define PG8_WAIT_V(n) asm volatile("s_waitcnt vmcnt(" #n ")" ::: "memory")
; #define PG8_WAIT_L(n) asm volatile("s_waitcnt lgkmcnt(" #n ")" ::: "memory")
; #define PG8_BAR __builtin_amdgcn_s_barrier()
; #define PG8_SCHED __builtin_amdgcn_sched_barrier(0)
; template <class Epi, class Sched, bool ALIGN_EPI = false, bool SP2 = false>
; __device__ __forceinline__ void gemm_phase(PG8_LAS unsigned char* lds, const Gemm g, const Sched S, const Epi E) {
;     ...
;         for (int t = 0; t < nt; t += 2) {
;             if constexpr (Epi::MIDT >= 0) { if (t == Epi::MIDT) E.mid(acc, cur, wr, fr); }
;             const bool last = (t == nt - 2);
;             const char* a1 = cA + (size_t)(t + 1) * kstep;
;             const char* a2 = last ? nA : cA + (size_t)(t + 2) * kstep; const char* b2 = last ? nB : cB + (size_t)(t + 2) * kstep;
;     ...
;             PG8_LDA(At, 1, 1); PG8_STAGE(PG8_SB(1, 0), b3, voffB); PG8_STAGE(PG8_SB(1, 1), b3 + hstep, voffB); PG8_STAGE(PG8_SA(1, 0), a3, voffA);
;             PG8_WAIT_V(8); PG8_WAIT_L(0); PG8_BAR; PG8_MMA(1, 0, At, B0); PG8_MMA(1, 1, At, B1); PG8_BAR; PG8_SCHED;
	s_add_i32 s10, s14, s8
	v_lshl_add_u64 v[6:7], v[166:167], 0, s[18:19]
	s_mov_b32 m0, s10
	ds_read_b128 v[210:213], v173 offset:49152
	ds_read_b128 v[214:217], v173 offset:50176
	ds_read_b128 v[218:221], v173 offset:51200
	ds_read_b128 v[222:225], v173 offset:52224
	ds_read_b128 v[226:229], v173 offset:53248
	ds_read_b128 v[230:233], v173 offset:54272
	ds_read_b128 v[234:237], v173 offset:55296
	ds_read_b128 v[238:241], v173 offset:56320
	global_load_lds_dwordx4 v[6:7], off
	s_add_i32 m0, s10, 0x2000
	s_add_u32 s6, s6, 0x40080
	v_lshl_add_u64 v[6:7], v[184:185], 0, s[18:19]
	s_addc_u32 s7, s7, 0
	s_add_i32 s10, s15, s8
	global_load_lds_dwordx4 v[6:7], off
	v_lshl_add_u64 v[6:7], s[6:7], 0, v[150:151]
	s_mov_b32 m0, s10
	s_nop 0
	global_load_lds_dwordx4 v[6:7], off
	v_lshl_add_u64 v[6:7], s[6:7], 0, v[154:155]
	s_add_i32 m0, s10, 0x2000
	s_nop 0
	global_load_lds_dwordx4 v[6:7], off
	v_lshl_add_u64 v[6:7], v[186:187], 0, s[18:19]
	s_mov_b32 m0, s55
	s_nop 0
	global_load_lds_dwordx4 v[6:7], off
	v_lshl_add_u64 v[6:7], v[242:243], 0, s[18:19]
	s_mov_b32 m0, s58
	s_nop 0
	global_load_lds_dwordx4 v[6:7], off
	s_waitcnt vmcnt(8)
	s_waitcnt lgkmcnt(0)
	s_barrier
	s_setprio 1
	s_waitcnt lgkmcnt(0)
	v_mfma_f32_16x16x32_bf16 v[64:67], v[120:123], v[210:213], v[64:67]
	v_mfma_f32_16x16x32_bf16 v[60:63], v[180:183], v[210:213], v[60:63]
	v_mfma_f32_16x16x32_bf16 v[48:51], v[120:123], v[218:221], v[48:51]
	v_mfma_f32_16x16x32_bf16 v[44:47], v[180:183], v[218:221], v[44:47]
	v_mfma_f32_16x16x32_bf16 v[32:35], v[120:123], v[226:229], v[32:35]
	v_mfma_f32_16x16x32_bf16 v[28:31], v[180:183], v[226:229], v[28:31]
	v_mfma_f32_16x16x32_bf16 v[16:19], v[120:123], v[234:237], v[16:19]
	v_mfma_f32_16x16x32_bf16 v[12:15], v[180:183], v[234:237], v[12:15]
	v_mfma_f32_16x16x32_bf16 v[64:67], v[176:179], v[214:217], v[64:67]
	v_mfma_f32_16x16x32_bf16 v[60:63], v[190:193], v[214:217], v[60:63]
	v_mfma_f32_16x16x32_bf16 v[48:51], v[176:179], v[222:225], v[48:51]
	v_mfma_f32_16x16x32_bf16 v[44:47], v[190:193], v[222:225], v[44:47]
	v_mfma_f32_16x16x32_bf16 v[32:35], v[176:179], v[230:233], v[32:35]
	v_mfma_f32_16x16x32_bf16 v[28:31], v[190:193], v[230:233], v[28:31]
	v_mfma_f32_16x16x32_bf16 v[16:19], v[176:179], v[238:241], v[16:19]
	v_mfma_f32_16x16x32_bf16 v[12:15], v[190:193], v[238:241], v[12:15]
	s_setprio 0
	s_setprio 1
	v_mfma_f32_16x16x32_bf16 v[56:59], v[194:197], v[210:213], v[56:59]
	v_mfma_f32_16x16x32_bf16 v[52:55], v[202:205], v[210:213], v[52:55]
	v_mfma_f32_16x16x32_bf16 v[40:43], v[194:197], v[218:221], v[40:43]
	v_mfma_f32_16x16x32_bf16 v[36:39], v[202:205], v[218:221], v[36:39]
	v_mfma_f32_16x16x32_bf16 v[24:27], v[194:197], v[226:229], v[24:27]
	v_mfma_f32_16x16x32_bf16 v[20:23], v[202:205], v[226:229], v[20:23]
	v_mfma_f32_16x16x32_bf16 v[6:9], v[194:197], v[234:237], v[8:11]
	v_mfma_f32_16x16x32_bf16 v[2:5], v[202:205], v[234:237], v[2:5]
	v_mfma_f32_16x16x32_bf16 v[56:59], v[198:201], v[214:217], v[56:59]
	v_mfma_f32_16x16x32_bf16 v[52:55], v[206:209], v[214:217], v[52:55]
	v_mfma_f32_16x16x32_bf16 v[40:43], v[198:201], v[222:225], v[40:43]
	v_mfma_f32_16x16x32_bf16 v[36:39], v[206:209], v[222:225], v[36:39]
	s_add_i32 s76, s76, 2
	s_add_u32 s70, s70, 0x100
	s_addc_u32 s71, s71, 0
	s_cmp_gt_u32 s76, 13
	v_mfma_f32_16x16x32_bf16 v[24:27], v[198:201], v[230:233], v[24:27]
	v_mfma_f32_16x16x32_bf16 v[20:23], v[206:209], v[230:233], v[20:23]
	v_mfma_f32_16x16x32_bf16 v[8:11], v[198:201], v[238:241], v[6:9]
	v_mfma_f32_16x16x32_bf16 v[4:7], v[206:209], v[238:241], v[2:5]
	s_setprio 0
	s_barrier
	s_cbranch_scc1 .LBB0_901
